# exchange step: 16 sc1 loads hoisted (plus spread K/V loads, subln hoist, single diff seam)
# speedup vs baseline: 1.0452x; 1.0130x over previous
; __device__ __forceinline__ unsigned xb_ld(unsigned* p)              { return __hip_atomic_load(p, __ATOMIC_RELAXED, __HIP_MEMORY_SCOPE_AGENT); }
; __device__ __forceinline__ unsigned xb_add(unsigned* p, unsigned v) { return __hip_atomic_fetch_add(p, v, __ATOMIC_RELAXED, __HIP_MEMORY_SCOPE_AGENT); }
; #define XB_SPIN(cond, bar) do { unsigned _sp = 0; while (cond) { __builtin_amdgcn_s_sleep(1); \
;     if ((++_sp & 255u) == 0u) { if (xb_ld(&(bar)[XB_TMO])) break; if (_sp > XB_SPIN_CAP) { atomicAdd(&(bar)[XB_TMO], 1u); break; } } } } while (0)
; #define SEAM(k) do { if (IN(k) && IN((k) + 1)) { if (ph_hi < 0) grid.sync(); else xcd_barrier(xbar); } } while (0)
; __device__ __forceinline__ void xcd_barrier(const XcdBarrier& b) {
;     asm volatile("s_waitcnt vmcnt(0)" ::: "memory");
;     __syncthreads();
;     if (threadIdx.x == 0) {
;         unsigned* bar = b.bar;
;         __builtin_amdgcn_s_waitcnt(0);
;         unsigned nloc = b.st[0], nx = b.st[1];
;         if (nloc == 0u) { xcd_barrier_complete(bar, b.x, nloc, nx); b.st[0] = nloc; b.st[1] = nx; }
;         const unsigned old = xb_add(&bar[XB_XSUB(b.x)], 1u);
;         const unsigned gen = old / nloc;
;         if (old + 1u == (gen + 1u) * nloc) {
;             __builtin_amdgcn_fence(__ATOMIC_RELEASE, "agent");
;             asm volatile("s_waitcnt vmcnt(0)" ::: "memory");
;             const unsigned og = xb_add(&bar[XB_TOP], 1u);
;             const unsigned tg = og / nx;
;             if (og + 1u == (tg + 1u) * nx) xb_add(&bar[XB_TOPGEN], 1u);
;             else XB_SPIN(xb_ld(&bar[XB_TOPGEN]) == tg, bar);
;             __builtin_amdgcn_fence(__ATOMIC_ACQUIRE, "agent");
;             xb_add(&bar[XB_XGEN(b.x)], 1u);
;             asm volatile("s_waitcnt vmcnt(0)" ::: "memory");
;         } else {
;             XB_SPIN(xb_ld(&bar[XB_XGEN(b.x)]) == gen, bar);
;             __builtin_amdgcn_fence(__ATOMIC_ACQUIRE, "agent");
;             asm volatile("s_waitcnt vmcnt(0)" ::: "memory");
;         }
;     }
;     __syncthreads();
; }
; __global__ void __launch_bounds__(NTHR, 2) fwd_mega(Args args_unused, int ph_lo, int ph_hi) {
;     ...
;             SEAM(pb);
;             SEAM(pb + 1);
;             MIXER_DIFF
;             SEAM(pb + 2);
.LBB0_157:
	s_add_i32 s4, s0, 2
.LBB0_224:
	s_cmp_le_i32 s58, s4
	s_cselect_b64 s[18:19], -1, 0
	s_cmp_lt_i32 s4, s59
	s_cselect_b64 s[22:23], -1, 0
	s_add_i32 s4, s0, 3
	s_cmp_lt_i32 s4, s59
	s_cselect_b64 s[6:7], -1, 0
	s_and_b64 s[22:23], s[22:23], s[6:7]
	s_and_b64 s[18:19], s[22:23], s[18:19]
	s_andn2_b64 vcc, exec, s[18:19]
	s_cbranch_vccnz .LBB0_292
	s_mov_b64 s[22:23], -1
	s_and_b64 vcc, exec, s[52:53]
	s_cbranch_vccz .LBB0_279
	s_waitcnt vmcnt(0)
	s_waitcnt vmcnt(0)
	s_barrier
	s_mov_b64 s[22:23], exec
	v_readlane_b32 s18, v254, 3
	v_readlane_b32 s19, v254, 4
	s_and_b64 s[18:19], s[22:23], s[18:19]
	s_mov_b64 exec, s[18:19]
	s_cbranch_execz .LBB0_278
	v_readlane_b32 s5, v254, 63
	s_waitcnt vmcnt(0) expcnt(0) lgkmcnt(0)
	s_nop 0
	v_mov_b32_e32 v0, s5
	ds_read_b32 v2, v0
	v_readlane_b32 s5, v255, 0
	s_waitcnt lgkmcnt(0)
	v_cmp_ne_u32_e32 vcc, 0, v2
	v_mov_b32_e32 v0, s5
	ds_read_b32 v0, v0
	s_cbranch_vccnz .LBB0_242
	s_mov_b32 s5, 1
	s_branch .LBB0_230

; __device__ __forceinline__ int crow(int i, int hh) { return (i & 3) + 8 * (i >> 2) + 4 * hh; }
; __device__ __forceinline__ unsigned cvtpk(float lo, float hi) { return pg8::cvt_pk_bf16(lo, hi); }
;     ...
;         if (mi == 0) { float ssq = 0.f;
; #pragma unroll
;             for (int dt = 0; dt < 4; ++dt)
; #pragma unroll
;                 for (int i = 0; i < 16; ++i) { const float v = o[dt][i] * linv - ex[g * 4096 + (32 * dt + crow(i, hh)) * 32 + r]; o[dt][i] = v; ssq += v * v; }
;             ssq += __shfl_xor(ssq, 32);
;             const float rstd = outscale / sqrtf(ssq * (1.0f / 128.0f) + RMS_EPS);
;             bf16* op = Od + ((size_t)(b * SEQ + qabs)) * 1024 + h * 128 + 4 * hh;
; #pragma unroll
;             for (int dt = 0; dt < 4; ++dt)
; #pragma unroll
;                 for (int i4 = 0; i4 < 4; ++i4) { const int dv = 32 * dt + 8 * i4; const f32x4 sg = *(const f32x4*)(subln + dv + 4 * hh);
;                     v2u wv; wv.x = cvtpk(o[dt][4 * i4] * rstd * sg[0], o[dt][4 * i4 + 1] * rstd * sg[1]); wv.y = cvtpk(o[dt][4 * i4 + 2] * rstd * sg[2], o[dt][4 * i4 + 3] * rstd * sg[3]);
;                     *(v2u*)(op + dv) = wv; }
.LBB0_312:
	s_andn2_b64 vcc, exec, s[28:29]
	s_waitcnt lgkmcnt(0)
	s_setprio 0
	s_barrier
	s_cbranch_vccnz .LBB0_296
	global_load_dwordx4 v[96:99], v[192:193], off
	global_load_dwordx4 v[100:103], v[192:193], off offset:32
	global_load_dwordx4 v[104:107], v[192:193], off offset:64
	global_load_dwordx4 v[108:111], v[192:193], off offset:96
	global_load_dwordx4 v[112:115], v[192:193], off offset:128
	global_load_dwordx4 v[116:119], v[192:193], off offset:160
	global_load_dwordx4 v[120:123], v[192:193], off offset:192
	global_load_dwordx4 v[124:127], v[192:193], off offset:224
	global_load_dwordx4 v[128:131], v[192:193], off offset:256
	global_load_dwordx4 v[132:135], v[192:193], off offset:288
	global_load_dwordx4 v[136:139], v[192:193], off offset:320
	global_load_dwordx4 v[140:143], v[192:193], off offset:352
	global_load_dwordx4 v[144:147], v[192:193], off offset:384
	global_load_dwordx4 v[148:151], v[192:193], off offset:416
	global_load_dwordx4 v[152:155], v[192:193], off offset:448
	global_load_dwordx4 v[156:159], v[192:193], off offset:480
	ds_read2_b32 v[38:39], v224 offset1:32
	ds_read2_b32 v[40:41], v42 offset1:32
	ds_read2_b32 v[42:43], v42 offset0:64 offset1:96
	s_waitcnt lgkmcnt(2)
	v_fma_f32 v37, v64, v36, -v38
	v_fma_f32 v33, v65, v36, -v39
	ds_read2_b32 v[38:39], v224 offset0:64 offset1:96
	ds_read2_b32 v[64:65], v46 offset1:32
	ds_read2_b32 v[46:47], v46 offset0:64 offset1:96
	s_waitcnt lgkmcnt(3)
	v_fma_f32 v42, v70, v36, -v42
	v_fma_f32 v43, v71, v36, -v43
	s_waitcnt lgkmcnt(2)
	v_fma_f32 v38, v66, v36, -v38
	v_fma_f32 v39, v67, v36, -v39
	ds_read2_b32 v[66:67], v93 offset1:32
	s_waitcnt lgkmcnt(2)
	v_fma_f32 v45, v72, v36, -v64
	v_fma_f32 v44, v73, v36, -v65
	s_waitcnt lgkmcnt(1)
	v_fma_f32 v65, v74, v36, -v46
	v_fma_f32 v64, v75, v36, -v47
	s_waitcnt lgkmcnt(0)
	v_fma_f32 v47, v76, v36, -v66
	v_fma_f32 v46, v77, v36, -v67
	ds_read2_b32 v[66:67], v93 offset0:64 offset1:96
	ds_read2_b32 v[70:71], v92 offset1:32
	v_fma_f32 v40, v68, v36, -v40
	v_fma_f32 v41, v69, v36, -v41
	ds_read2_b32 v[72:73], v90 offset1:32
	s_waitcnt lgkmcnt(2)
	v_fma_f32 v68, v78, v36, -v66
	s_waitcnt lgkmcnt(1)
	v_fma_f32 v66, v48, v36, -v70
	v_fma_f32 v48, v49, v36, -v71
	ds_read2_b32 v[70:71], v92 offset0:64 offset1:96
	v_mul_f32_e32 v84, v33, v33
	v_fmac_f32_e32 v84, v37, v37
	v_fmac_f32_e32 v84, v38, v38
	v_fmac_f32_e32 v84, v39, v39
	s_waitcnt lgkmcnt(0)
	v_fma_f32 v69, v50, v36, -v70
	v_fma_f32 v51, v51, v36, -v71
	ds_read2_b32 v[70:71], v91 offset1:32
	v_fmac_f32_e32 v84, v40, v40
	v_fmac_f32_e32 v84, v41, v41
	v_fmac_f32_e32 v84, v42, v42
	v_fmac_f32_e32 v84, v43, v43
	s_waitcnt lgkmcnt(0)
	v_fma_f32 v50, v52, v36, -v70
	v_fma_f32 v49, v53, v36, -v71
	ds_read2_b32 v[52:53], v91 offset0:64 offset1:96
	v_fmac_f32_e32 v84, v45, v45
	v_fmac_f32_e32 v84, v44, v44
	v_fmac_f32_e32 v84, v65, v65
	v_fmac_f32_e32 v84, v64, v64
	s_waitcnt lgkmcnt(0)
	v_fma_f32 v70, v54, v36, -v52
	v_fma_f32 v54, v55, v36, -v53
	v_fma_f32 v53, v56, v36, -v72
	v_fma_f32 v52, v57, v36, -v73
	ds_read2_b32 v[56:57], v90 offset0:64 offset1:96
	ds_read2_b32 v[72:73], v89 offset1:32
	v_fmac_f32_e32 v84, v47, v47
	v_fmac_f32_e32 v84, v46, v46
	v_fmac_f32_e32 v84, v68, v68
	s_waitcnt lgkmcnt(1)
	v_fma_f32 v58, v58, v36, -v56
	s_waitcnt lgkmcnt(0)
	v_fma_f32 v56, v60, v36, -v72
	v_fma_f32 v55, v61, v36, -v73
	ds_read2_b32 v[72:73], v89 offset0:64 offset1:96
	v_fma_f32 v57, v59, v36, -v57
	v_fma_f32 v67, v79, v36, -v67
	v_fmac_f32_e32 v84, v67, v67
	v_fmac_f32_e32 v84, v66, v66
	s_waitcnt lgkmcnt(0)
	v_fma_f32 v61, v62, v36, -v72
	v_fma_f32 v60, v63, v36, -v73
	ds_read2_b32 v[62:63], v88 offset1:32
	ds_read2_b32 v[72:73], v87 offset1:32
	v_fmac_f32_e32 v84, v48, v48
	v_fmac_f32_e32 v84, v69, v69
	v_fmac_f32_e32 v84, v51, v51
	s_waitcnt lgkmcnt(1)
	v_fma_f32 v59, v16, v36, -v62
	v_fma_f32 v16, v17, v36, -v63
	ds_read2_b32 v[62:63], v88 offset0:64 offset1:96
	s_waitcnt lgkmcnt(1)
	v_fma_f32 v17, v21, v36, -v73
	v_fmac_f32_e32 v84, v50, v50
	v_fmac_f32_e32 v84, v49, v49
	v_fmac_f32_e32 v84, v70, v70
	s_waitcnt lgkmcnt(0)
	v_fma_f32 v62, v18, v36, -v62
	v_fma_f32 v18, v20, v36, -v72
	ds_read2_b32 v[20:21], v87 offset0:64 offset1:96
	ds_read2_b32 v[72:73], v86 offset1:32
	v_fma_f32 v19, v19, v36, -v63
	v_fmac_f32_e32 v84, v54, v54
	v_fmac_f32_e32 v84, v53, v53
	s_waitcnt lgkmcnt(1)
	v_fma_f32 v63, v22, v36, -v20
	v_fma_f32 v22, v23, v36, -v21
	s_waitcnt lgkmcnt(0)
	v_fma_f32 v21, v24, v36, -v72
	v_fma_f32 v20, v25, v36, -v73
	ds_read2_b32 v[24:25], v86 offset0:64 offset1:96
	ds_read2_b32 v[72:73], v85 offset1:32
	v_fmac_f32_e32 v84, v52, v52
	v_fmac_f32_e32 v84, v58, v58
	v_fmac_f32_e32 v84, v57, v57
	s_waitcnt lgkmcnt(1)
	v_fma_f32 v26, v26, v36, -v24
	s_waitcnt lgkmcnt(0)
	v_fma_f32 v24, v28, v36, -v72
	v_fma_f32 v23, v29, v36, -v73
	ds_read2_b32 v[28:29], v85 offset0:64 offset1:96
	ds_read2_b32 v[72:73], v83 offset1:32
	v_fmac_f32_e32 v84, v56, v56
	v_fma_f32 v25, v27, v36, -v25
	v_fmac_f32_e32 v84, v55, v55
	s_waitcnt lgkmcnt(1)
	v_fma_f32 v71, v30, v36, -v28
	v_fma_f32 v30, v31, v36, -v29
	s_waitcnt lgkmcnt(0)
	v_fma_f32 v29, v0, v36, -v72
	v_fma_f32 v27, v1, v36, -v73
	ds_read2_b32 v[0:1], v83 offset0:64 offset1:96
	v_fmac_f32_e32 v84, v61, v61
	v_fmac_f32_e32 v84, v60, v60
	v_fmac_f32_e32 v84, v59, v59
	v_fmac_f32_e32 v84, v16, v16
	s_waitcnt lgkmcnt(0)
	v_fma_f32 v77, v2, v36, -v0
	v_fma_f32 v76, v3, v36, -v1
	ds_read2_b32 v[0:1], v82 offset1:32
	v_fmac_f32_e32 v84, v62, v62
	v_fmac_f32_e32 v84, v19, v19
	v_fmac_f32_e32 v84, v18, v18
	v_fmac_f32_e32 v84, v17, v17
	v_fmac_f32_e32 v84, v63, v63
	s_waitcnt lgkmcnt(0)
; __device__ __forceinline__ unsigned cvtpk(float lo, float hi) { return pg8::cvt_pk_bf16(lo, hi); }
;     ...
;             ssq += __shfl_xor(ssq, 32);
;             const float rstd = outscale / sqrtf(ssq * (1.0f / 128.0f) + RMS_EPS);
;             bf16* op = Od + ((size_t)(b * SEQ + qabs)) * 1024 + h * 128 + 4 * hh;
; #pragma unroll
;             for (int dt = 0; dt < 4; ++dt)
; #pragma unroll
;                 for (int i4 = 0; i4 < 4; ++i4) { const int dv = 32 * dt + 8 * i4; const f32x4 sg = *(const f32x4*)(subln + dv + 4 * hh);
;                     v2u wv; wv.x = cvtpk(o[dt][4 * i4] * rstd * sg[0], o[dt][4 * i4 + 1] * rstd * sg[1]); wv.y = cvtpk(o[dt][4 * i4 + 2] * rstd * sg[2], o[dt][4 * i4 + 3] * rstd * sg[3]);
;                     *(v2u*)(op + dv) = wv; }
	v_fma_f32 v74, v4, v36, -v0
	v_fma_f32 v73, v5, v36, -v1
	ds_read2_b32 v[0:1], v82 offset0:64 offset1:96
	v_fmac_f32_e32 v84, v22, v22
	v_fmac_f32_e32 v84, v21, v21
	v_fmac_f32_e32 v84, v20, v20
	v_fmac_f32_e32 v84, v26, v26
	v_fmac_f32_e32 v84, v25, v25
	s_waitcnt lgkmcnt(0)
	v_fma_f32 v78, v6, v36, -v0
	v_fma_f32 v75, v7, v36, -v1
	ds_read2_b32 v[0:1], v81 offset1:32
	v_fmac_f32_e32 v84, v24, v24
	v_fmac_f32_e32 v84, v23, v23
	v_fmac_f32_e32 v84, v71, v71
	v_fmac_f32_e32 v84, v30, v30
	v_fmac_f32_e32 v84, v29, v29
	s_waitcnt lgkmcnt(0)
	v_fma_f32 v72, v8, v36, -v0
	v_fma_f32 v31, v9, v36, -v1
	ds_read2_b32 v[0:1], v81 offset0:64 offset1:96
	v_fmac_f32_e32 v84, v27, v27
	v_fmac_f32_e32 v84, v77, v77
	v_fmac_f32_e32 v84, v76, v76
	v_fmac_f32_e32 v84, v74, v74
	v_fmac_f32_e32 v84, v73, v73
	s_waitcnt lgkmcnt(0)
	v_fma_f32 v28, v10, v36, -v0
	v_fma_f32 v10, v11, v36, -v1
	ds_read2_b32 v[0:1], v80 offset1:32
	v_fmac_f32_e32 v84, v78, v78
	v_fmac_f32_e32 v84, v75, v75
	v_fmac_f32_e32 v84, v72, v72
	v_fmac_f32_e32 v84, v31, v31
	v_fmac_f32_e32 v84, v28, v28
	s_waitcnt lgkmcnt(0)
	v_pk_fma_f32 v[6:7], v[12:13], v[36:37], v[0:1] op_sel_hi:[1,0,1] neg_lo:[0,0,1] neg_hi:[0,0,1]
	v_fmac_f32_e32 v84, v10, v10
	v_pk_mul_f32 v[0:1], v[6:7], v[6:7]
	s_nop 0
	v_add_f32_e32 v0, v84, v0
	v_add_f32_e32 v2, v0, v1
	ds_read2_b32 v[0:1], v80 offset0:64 offset1:96
	s_waitcnt lgkmcnt(0)
	v_pk_fma_f32 v[4:5], v[14:15], v[36:37], v[0:1] op_sel_hi:[1,0,1] neg_lo:[0,0,1] neg_hi:[0,0,1]
	s_nop 0
	v_pk_mul_f32 v[0:1], v[4:5], v[4:5]
	s_nop 0
	v_add_f32_e32 v0, v2, v0
	v_and_b32_e32 v2, 64, v233
	v_add_f32_e32 v0, v0, v1
	v_xor_b32_e32 v1, 32, v233
	v_add_u32_e32 v2, 64, v2
	v_cmp_lt_i32_e32 vcc, v1, v2
	s_nop 1
	v_cndmask_b32_e32 v1, v233, v1, vcc
	v_lshlrev_b32_e32 v1, 2, v1
	ds_bpermute_b32 v1, v1, v0
	s_waitcnt lgkmcnt(0)
	v_add_f32_e32 v0, v0, v1
	v_fmamk_f32 v0, v0, 0x3c000000, v231
	v_cmp_gt_f32_e32 vcc, s73, v0
	v_mul_f32_e32 v1, 0x4f800000, v0
	s_nop 0
	v_cndmask_b32_e32 v0, v0, v1, vcc
	v_sqrt_f32_e32 v1, v0
	s_nop 0
	v_add_u32_e32 v2, -1, v1
	v_fma_f32 v3, -v2, v1, v0
	v_cmp_ge_f32_e64 s[40:41], 0, v3
	v_add_u32_e32 v3, 1, v1
	s_nop 0
	v_cndmask_b32_e64 v2, v1, v2, s[40:41]
	v_fma_f32 v1, -v3, v1, v0
	v_cmp_lt_f32_e64 s[40:41], 0, v1
	s_nop 1
	v_cndmask_b32_e64 v1, v2, v3, s[40:41]
	v_mul_f32_e32 v2, 0x37800000, v1
	v_cndmask_b32_e32 v1, v1, v2, vcc
	v_cmp_class_f32_e32 vcc, v0, v232
	s_nop 1
	v_cndmask_b32_e32 v0, v1, v0, vcc
	v_div_scale_f32 v1, s[4:5], v0, v0, v215
	v_rcp_f32_e32 v2, v1
	s_nop 0
	v_fma_f32 v3, -v1, v2, 1.0
	v_fmac_f32_e32 v2, v3, v2
	v_div_scale_f32 v3, vcc, v215, v0, v215
	v_mul_f32_e32 v8, v3, v2
	v_fma_f32 v9, -v1, v8, v3
	v_fmac_f32_e32 v8, v9, v2
	v_fma_f32 v1, -v1, v8, v3
	v_div_fmas_f32 v1, v1, v2, v8
	v_div_fixup_f32 v11, v1, v0, v215
	v_mul_f32_e32 v12, v37, v11
	v_lshl_add_u64 v[8:9], v[34:35], 1, v[190:191]
	v_mul_f32_e32 v6, v6, v11
	s_waitcnt vmcnt(15)
	v_mul_f32_e32 v0, v96, v12
	v_mul_f32_e32 v12, v33, v11
	v_mul_f32_e32 v1, v97, v12
	v_cvt_pk_bf16_f32 v0, v0, v1
	v_mul_f32_e32 v1, v38, v11
	v_mul_f32_e32 v1, v98, v1
	v_mul_f32_e32 v2, v39, v11
	v_mul_f32_e32 v2, v99, v2
	v_cvt_pk_bf16_f32 v1, v1, v2
	global_store_dwordx2 v[8:9], v[0:1], off
	v_mul_f32_e32 v12, v40, v11
	s_waitcnt vmcnt(15)
	v_mul_f32_e32 v0, v100, v12
	v_mul_f32_e32 v12, v41, v11
	v_mul_f32_e32 v1, v101, v12
	v_cvt_pk_bf16_f32 v0, v0, v1
	v_mul_f32_e32 v1, v42, v11
	v_mul_f32_e32 v1, v102, v1
	v_mul_f32_e32 v2, v43, v11
	v_mul_f32_e32 v2, v103, v2
	v_cvt_pk_bf16_f32 v1, v1, v2
	global_store_dwordx2 v[8:9], v[0:1], off offset:16
	v_mul_f32_e32 v12, v45, v11
	s_waitcnt vmcnt(15)
	v_mul_f32_e32 v0, v12, v104
	v_mul_f32_e32 v12, v44, v11
	v_mul_f32_e32 v1, v12, v105
	v_cvt_pk_bf16_f32 v0, v0, v1
	v_mul_f32_e32 v1, v65, v11
	v_mul_f32_e32 v1, v1, v106
	v_mul_f32_e32 v2, v64, v11
	v_mul_f32_e32 v2, v2, v107
	v_cvt_pk_bf16_f32 v1, v1, v2
	global_store_dwordx2 v[8:9], v[0:1], off offset:32
	v_mul_f32_e32 v12, v47, v11
	s_waitcnt vmcnt(15)
	v_mul_f32_e32 v0, v12, v108
	v_mul_f32_e32 v12, v46, v11
	v_mul_f32_e32 v1, v12, v109
	v_cvt_pk_bf16_f32 v0, v0, v1
	v_mul_f32_e32 v1, v68, v11
	v_mul_f32_e32 v1, v1, v110
	v_mul_f32_e32 v2, v67, v11
	v_mul_f32_e32 v2, v2, v111
	v_cvt_pk_bf16_f32 v1, v1, v2
	global_store_dwordx2 v[8:9], v[0:1], off offset:48
	v_mul_f32_e32 v12, v66, v11
	s_waitcnt vmcnt(15)
; __device__ __forceinline__ unsigned cvtpk(float lo, float hi) { return pg8::cvt_pk_bf16(lo, hi); }
;     ...
;             for (int dt = 0; dt < 4; ++dt)
; #pragma unroll
;                 for (int i4 = 0; i4 < 4; ++i4) { const int dv = 32 * dt + 8 * i4; const f32x4 sg = *(const f32x4*)(subln + dv + 4 * hh);
;                     v2u wv; wv.x = cvtpk(o[dt][4 * i4] * rstd * sg[0], o[dt][4 * i4 + 1] * rstd * sg[1]); wv.y = cvtpk(o[dt][4 * i4 + 2] * rstd * sg[2], o[dt][4 * i4 + 3] * rstd * sg[3]);
;                     *(v2u*)(op + dv) = wv; }
	v_mul_f32_e32 v0, v12, v112
	v_mul_f32_e32 v12, v48, v11
	v_mul_f32_e32 v1, v12, v113
	v_cvt_pk_bf16_f32 v0, v0, v1
	v_mul_f32_e32 v1, v69, v11
	v_mul_f32_e32 v1, v1, v114
	v_mul_f32_e32 v2, v51, v11
	v_mul_f32_e32 v2, v2, v115
	v_cvt_pk_bf16_f32 v1, v1, v2
	global_store_dwordx2 v[8:9], v[0:1], off offset:64
	v_mul_f32_e32 v12, v50, v11
	s_waitcnt vmcnt(15)
	v_mul_f32_e32 v0, v12, v116
	v_mul_f32_e32 v12, v49, v11
	v_mul_f32_e32 v1, v12, v117
	v_cvt_pk_bf16_f32 v0, v0, v1
	v_mul_f32_e32 v1, v70, v11
	v_mul_f32_e32 v1, v1, v118
	v_mul_f32_e32 v2, v54, v11
	v_mul_f32_e32 v2, v2, v119
	v_cvt_pk_bf16_f32 v1, v1, v2
	global_store_dwordx2 v[8:9], v[0:1], off offset:80
	v_mul_f32_e32 v12, v53, v11
	s_waitcnt vmcnt(15)
	v_mul_f32_e32 v0, v12, v120
	v_mul_f32_e32 v12, v52, v11
	v_mul_f32_e32 v1, v12, v121
	v_cvt_pk_bf16_f32 v0, v0, v1
	v_mul_f32_e32 v1, v58, v11
	v_mul_f32_e32 v1, v1, v122
	v_mul_f32_e32 v2, v57, v11
	v_mul_f32_e32 v2, v2, v123
	v_cvt_pk_bf16_f32 v1, v1, v2
	global_store_dwordx2 v[8:9], v[0:1], off offset:96
	v_mul_f32_e32 v12, v56, v11
	s_waitcnt vmcnt(15)
	v_mul_f32_e32 v0, v12, v124
	v_mul_f32_e32 v12, v55, v11
	v_mul_f32_e32 v1, v12, v125
	v_cvt_pk_bf16_f32 v0, v0, v1
	v_mul_f32_e32 v1, v61, v11
	v_mul_f32_e32 v1, v1, v126
	v_mul_f32_e32 v2, v60, v11
	v_mul_f32_e32 v2, v2, v127
	v_cvt_pk_bf16_f32 v1, v1, v2
	global_store_dwordx2 v[8:9], v[0:1], off offset:112
	v_mul_f32_e32 v12, v59, v11
	s_waitcnt vmcnt(15)
	v_mul_f32_e32 v0, v12, v128
	v_mul_f32_e32 v12, v16, v11
	v_mul_f32_e32 v1, v12, v129
	v_cvt_pk_bf16_f32 v0, v0, v1
	v_mul_f32_e32 v1, v62, v11
	v_mul_f32_e32 v1, v1, v130
	v_mul_f32_e32 v2, v19, v11
	v_mul_f32_e32 v2, v2, v131
	v_cvt_pk_bf16_f32 v1, v1, v2
	global_store_dwordx2 v[8:9], v[0:1], off offset:128
	v_mul_f32_e32 v12, v18, v11
	s_waitcnt vmcnt(15)
	v_mul_f32_e32 v0, v12, v132
	v_mul_f32_e32 v12, v17, v11
	v_mul_f32_e32 v1, v12, v133
	v_cvt_pk_bf16_f32 v0, v0, v1
	v_mul_f32_e32 v1, v63, v11
	v_mul_f32_e32 v1, v1, v134
	v_mul_f32_e32 v2, v22, v11
	v_mul_f32_e32 v2, v2, v135
	v_cvt_pk_bf16_f32 v1, v1, v2
	global_store_dwordx2 v[8:9], v[0:1], off offset:144
	v_mul_f32_e32 v12, v21, v11
	s_waitcnt vmcnt(15)
	v_mul_f32_e32 v0, v12, v136
	v_mul_f32_e32 v12, v20, v11
	v_mul_f32_e32 v1, v12, v137
	v_cvt_pk_bf16_f32 v0, v0, v1
	v_mul_f32_e32 v1, v26, v11
	v_mul_f32_e32 v1, v1, v138
	v_mul_f32_e32 v2, v25, v11
	v_mul_f32_e32 v2, v2, v139
	v_cvt_pk_bf16_f32 v1, v1, v2
	global_store_dwordx2 v[8:9], v[0:1], off offset:160
	v_mul_f32_e32 v12, v24, v11
	s_waitcnt vmcnt(15)
	v_mul_f32_e32 v0, v12, v140
	v_mul_f32_e32 v12, v23, v11
	v_mul_f32_e32 v1, v12, v141
	v_cvt_pk_bf16_f32 v0, v0, v1
	v_mul_f32_e32 v1, v71, v11
	v_mul_f32_e32 v1, v1, v142
	v_mul_f32_e32 v2, v30, v11
	v_mul_f32_e32 v2, v2, v143
	v_cvt_pk_bf16_f32 v1, v1, v2
	global_store_dwordx2 v[8:9], v[0:1], off offset:176
	v_mul_f32_e32 v12, v29, v11
	s_waitcnt vmcnt(15)
	v_mul_f32_e32 v0, v12, v144
	v_mul_f32_e32 v12, v27, v11
	v_mul_f32_e32 v1, v12, v145
	v_cvt_pk_bf16_f32 v0, v0, v1
	v_mul_f32_e32 v1, v77, v11
	v_mul_f32_e32 v1, v1, v146
	v_mul_f32_e32 v2, v76, v11
	v_mul_f32_e32 v2, v2, v147
	v_cvt_pk_bf16_f32 v1, v1, v2
	global_store_dwordx2 v[8:9], v[0:1], off offset:192
	v_mul_f32_e32 v12, v74, v11
	s_waitcnt vmcnt(15)
	v_mul_f32_e32 v0, v12, v148
	v_mul_f32_e32 v12, v73, v11
	v_mul_f32_e32 v1, v12, v149
	v_cvt_pk_bf16_f32 v0, v0, v1
	v_mul_f32_e32 v1, v78, v11
	v_mul_f32_e32 v1, v1, v150
	v_mul_f32_e32 v2, v75, v11
	v_mul_f32_e32 v2, v2, v151
	v_cvt_pk_bf16_f32 v1, v1, v2
	global_store_dwordx2 v[8:9], v[0:1], off offset:208
	v_mul_f32_e32 v12, v72, v11
	s_waitcnt vmcnt(15)
	v_mul_f32_e32 v0, v12, v152
	v_mul_f32_e32 v12, v31, v11
	v_mul_f32_e32 v1, v12, v153
	v_cvt_pk_bf16_f32 v0, v0, v1
	v_mul_f32_e32 v1, v28, v11
	v_mul_f32_e32 v1, v1, v154
	v_mul_f32_e32 v2, v10, v11
	v_mul_f32_e32 v2, v2, v155
	v_cvt_pk_bf16_f32 v1, v1, v2
	global_store_dwordx2 v[8:9], v[0:1], off offset:224
	s_waitcnt vmcnt(15)
	v_mul_f32_e32 v0, v6, v156
	v_mul_f32_e32 v6, v7, v11
	v_mul_f32_e32 v1, v6, v157
	v_cvt_pk_bf16_f32 v0, v0, v1
	v_mul_f32_e32 v1, v4, v11
	v_mul_f32_e32 v1, v1, v158
	v_mul_f32_e32 v2, v5, v11
	v_mul_f32_e32 v2, v2, v159
	v_cvt_pk_bf16_f32 v1, v1, v2
	global_store_dwordx2 v[8:9], v[0:1], off offset:240
	s_branch .LBB0_296

; #define AT_LOADK(t) do { kr0 = *(const v4u*)(kg + (size_t)(t) * 64 * 1024); kr1 = *(const v4u*)(kg + (size_t)(t) * 64 * 1024 + 32 * 1024); } while (0)
; #define AT_LOADV(t) do { vr0 = *(const v4u*)(vg + (t) * 64); vr1 = *(const v4u*)(vg + (size_t)64 * SEQ + (t) * 64); } while (0)
; #define AT_STOREK(bf) do { *(LAS v4u*)(lds + (bf) * AT_KBUF + kso) = kr0; *(LAS v4u*)(lds + (bf) * AT_KBUF + kso + 32 * AT_KSTR * 2) = kr1; } while (0)
; #define AT_STOREV(bf) do { *(LAS v2u*)(lds + (bf) * AT_VBUF + vso) = (v2u){vr0.x, vr0.y}; *(LAS v2u*)(lds + (bf) * AT_VBUF + vso + 8) = (v2u){vr0.z, vr0.w}; \
;         *(LAS v2u*)(lds + (bf) * AT_VBUF + vso + 64 * AT_VSTR * 2) = (v2u){vr1.x, vr1.y}; *(LAS v2u*)(lds + (bf) * AT_VBUF + vso + 64 * AT_VSTR * 2 + 8) = (v2u){vr1.z, vr1.w}; } while (0)
;     ...
;             if (!(AMODE & 4) && t >= 1) { if (t + 1 < NT) AT_STOREK((t + 1) & 1); if (t < NT) AT_STOREV(t & 1); }
;             __syncthreads();
;             if (!(AMODE & 4)) { if (t + 2 < NT) AT_LOADK(t + 2); if (t + 1 < NT) AT_LOADV(t + 1); }
.LBB0_393:
	s_bitcmp1_b32 s50, 0
	s_cselect_b32 s49, 0x4400, 0
	v_add_u32_e32 v33, s49, v220
	v_add_u32_e32 v34, 0x8800, v33
	v_add_u32_e32 v33, 0xaa00, v33
	s_cmp_ge_i32 s50, s4
	s_waitcnt vmcnt(1)
	ds_write2_b64 v34, v[168:169], v[170:171] offset1:1
	s_waitcnt vmcnt(0)
	ds_write2_b64 v33, v[172:173], v[174:175] offset1:1
	s_waitcnt lgkmcnt(0)
	s_barrier
	s_setprio 1
	global_load_dwordx4 v[160:163], v[216:217], off
	s_mov_b64 s[66:67], 0x10000
	s_and_b64 vcc, exec, s[6:7]
	s_cbranch_vccz .LBB0_400
.LBB0_399:
	v_lshl_add_u64 v[252:253], v[216:217], 0, s[66:67]
	global_load_dwordx4 v[164:167], v[252:253], off
	v_lshl_add_u64 v[252:253], s[94:95], 1, v[178:179]
	global_load_dwordx4 v[168:171], v[252:253], off
	v_lshl_add_u64 v[252:253], s[94:95], 1, v[184:185]
	global_load_dwordx4 v[172:175], v[252:253], off
	s_setprio 0
	s_barrier
	s_cbranch_execnz .LBB0_469

.LBB0_466:
	v_max3_f32 v33, v96, v97, v80
	v_max3_f32 v34, v98, v99, v81
	s_mov_b32 s6, 0x40c00000
	v_max3_f32 v33, v33, v82, v83
	v_max3_f32 v34, v34, v102, v103
	v_lshl_add_u64 v[252:253], v[216:217], 0, s[66:67]
	global_load_dwordx4 v[164:167], v[252:253], off
	s_nop 0
	v_max3_f32 v33, v33, v100, v101
	v_max3_f32 v34, v34, v86, v87
	s_nop 0
	v_max3_f32 v33, v33, v84, v85
	v_max3_f32 v34, v34, v106, v107
	s_nop 0
	v_max3_f32 v33, v33, v104, v105
	v_max3_f32 v34, v34, v90, v91
	s_nop 0
	v_max3_f32 v33, v33, v88, v89
	v_max3_f32 v34, v34, v110, v111
	s_nop 0
	v_max3_f32 v33, v33, v108, v109
	v_max3_f32 v34, v34, v94, v95
	s_nop 0
	v_max3_f32 v33, v33, v92, v93
	v_max_f32_e32 v34, v34, v34
	v_max_f32_e32 v33, v33, v33
	v_max_f32_e32 v33, v33, v34
	v_mov_b32_e32 v34, v33
	s_nop 1
	v_permlane32_swap_b32_e32 v33, v34
	v_max_f32_e32 v34, v34, v34
	v_max_f32_e32 v33, v33, v33
	v_max_f32_e32 v33, v33, v34
	v_sub_f32_e32 v33, v33, v214
	v_cmp_lt_f32_e32 vcc, s6, v33
	s_or_b64 s[6:7], s[40:41], vcc
	v_cndmask_b32_e64 v34, 0, 1, s[6:7]
	v_cmp_ne_u32_e32 vcc, 0, v34
	s_cbranch_vccz .LBB0_468
	v_max_f32_e32 v34, v33, v33
	v_max_f32_e32 v34, 0, v34
	v_cndmask_b32_e64 v33, v34, v33, s[40:41]
	v_exp_f32_e64 v34, -v33
	v_add_f32_e32 v214, v214, v33
	v_cndmask_b32_e64 v34, v34, 1.0, s[40:41]
	v_pk_mul_f32 v[78:79], v[78:79], v[34:35] op_sel_hi:[1,0]
	v_pk_mul_f32 v[76:77], v[76:77], v[34:35] op_sel_hi:[1,0]
	v_pk_mul_f32 v[74:75], v[74:75], v[34:35] op_sel_hi:[1,0]
	v_pk_mul_f32 v[72:73], v[72:73], v[34:35] op_sel_hi:[1,0]
	v_pk_mul_f32 v[70:71], v[70:71], v[34:35] op_sel_hi:[1,0]
	v_pk_mul_f32 v[68:69], v[68:69], v[34:35] op_sel_hi:[1,0]
	v_pk_mul_f32 v[66:67], v[66:67], v[34:35] op_sel_hi:[1,0]
	v_pk_mul_f32 v[64:65], v[64:65], v[34:35] op_sel_hi:[1,0]
	v_pk_mul_f32 v[62:63], v[62:63], v[34:35] op_sel_hi:[1,0]
	v_pk_mul_f32 v[60:61], v[60:61], v[34:35] op_sel_hi:[1,0]
	v_pk_mul_f32 v[58:59], v[58:59], v[34:35] op_sel_hi:[1,0]
	v_pk_mul_f32 v[56:57], v[56:57], v[34:35] op_sel_hi:[1,0]
	v_pk_mul_f32 v[54:55], v[54:55], v[34:35] op_sel_hi:[1,0]
	v_pk_mul_f32 v[52:53], v[52:53], v[34:35] op_sel_hi:[1,0]
	v_pk_mul_f32 v[50:51], v[50:51], v[34:35] op_sel_hi:[1,0]
	v_pk_mul_f32 v[48:49], v[48:49], v[34:35] op_sel_hi:[1,0]
	v_pk_mul_f32 v[30:31], v[30:31], v[34:35] op_sel_hi:[1,0]
	v_pk_mul_f32 v[28:29], v[28:29], v[34:35] op_sel_hi:[1,0]
	v_pk_mul_f32 v[26:27], v[26:27], v[34:35] op_sel_hi:[1,0]
	v_pk_mul_f32 v[24:25], v[24:25], v[34:35] op_sel_hi:[1,0]
	v_pk_mul_f32 v[22:23], v[22:23], v[34:35] op_sel_hi:[1,0]
	v_pk_mul_f32 v[20:21], v[20:21], v[34:35] op_sel_hi:[1,0]
	v_pk_mul_f32 v[18:19], v[18:19], v[34:35] op_sel_hi:[1,0]
	v_pk_mul_f32 v[16:17], v[16:17], v[34:35] op_sel_hi:[1,0]
	v_pk_mul_f32 v[14:15], v[14:15], v[34:35] op_sel_hi:[1,0]
	v_pk_mul_f32 v[12:13], v[12:13], v[34:35] op_sel_hi:[1,0]
	v_pk_mul_f32 v[10:11], v[10:11], v[34:35] op_sel_hi:[1,0]
	v_pk_mul_f32 v[8:9], v[8:9], v[34:35] op_sel_hi:[1,0]
	v_pk_mul_f32 v[6:7], v[6:7], v[34:35] op_sel_hi:[1,0]
	v_pk_mul_f32 v[4:5], v[4:5], v[34:35] op_sel_hi:[1,0]
	v_pk_mul_f32 v[2:3], v[2:3], v[34:35] op_sel_hi:[1,0]
	v_pk_mul_f32 v[0:1], v[0:1], v[34:35] op_sel_hi:[1,0]
	v_mul_f32_e32 v250, v250, v34
	s_mov_b64 s[40:41], 0
.LBB0_468:
	v_sub_f32_e32 v34, v96, v214
	v_sub_f32_e32 v35, v97, v214
	v_sub_f32_e32 v36, v80, v214
	v_sub_f32_e32 v37, v81, v214
	v_exp_f32_e32 v34, v34
	v_exp_f32_e32 v35, v35
	v_exp_f32_e32 v42, v36
	v_exp_f32_e32 v43, v37
	v_lshl_add_u64 v[252:253], s[94:95], 1, v[178:179]
	global_load_dwordx4 v[168:171], v[252:253], off
	v_sub_f32_e32 v38, v98, v214
	v_sub_f32_e32 v39, v99, v214
	v_sub_f32_e32 v40, v82, v214
	v_sub_f32_e32 v41, v83, v214
	v_exp_f32_e32 v38, v38
	v_exp_f32_e32 v39, v39
	v_exp_f32_e32 v44, v40
	v_exp_f32_e32 v45, v41
	v_sub_f32_e32 v40, v100, v214
	v_sub_f32_e32 v41, v101, v214
	v_add_f32_e32 v36, 0, v34
	v_add_f32_e32 v37, 0, v35
	v_sub_f32_e32 v46, v84, v214
	v_sub_f32_e32 v47, v85, v214
	v_exp_f32_e32 v40, v40
	v_exp_f32_e32 v41, v41
	v_add_f32_e32 v36, v42, v36
	v_add_f32_e32 v37, v43, v37
	v_exp_f32_e32 v46, v46
	v_exp_f32_e32 v47, v47
	v_sub_f32_e32 v80, v102, v214
	v_sub_f32_e32 v81, v103, v214
	v_add_f32_e32 v36, v38, v36
	v_add_f32_e32 v37, v39, v37
	v_sub_f32_e32 v82, v86, v214
	v_sub_f32_e32 v83, v87, v214
	v_exp_f32_e32 v80, v80
	v_exp_f32_e32 v81, v81
	v_add_f32_e32 v36, v44, v36
	v_add_f32_e32 v37, v45, v37
	v_exp_f32_e32 v82, v82
	v_exp_f32_e32 v83, v83
	v_lshl_add_u64 v[252:253], s[94:95], 1, v[184:185]
	global_load_dwordx4 v[172:175], v[252:253], off
	v_sub_f32_e32 v84, v104, v214
	v_sub_f32_e32 v85, v105, v214
	v_add_f32_e32 v36, v40, v36
	v_add_f32_e32 v37, v41, v37
	v_sub_f32_e32 v86, v88, v214
	v_sub_f32_e32 v87, v89, v214
	v_exp_f32_e32 v84, v84
	v_exp_f32_e32 v85, v85
	v_add_f32_e32 v36, v46, v36
	v_add_f32_e32 v37, v47, v37
	v_exp_f32_e32 v86, v86
	v_exp_f32_e32 v87, v87
	v_sub_f32_e32 v88, v106, v214
	v_sub_f32_e32 v89, v107, v214
	v_add_f32_e32 v36, v80, v36
	v_add_f32_e32 v37, v81, v37
	v_sub_f32_e32 v90, v90, v214
	v_sub_f32_e32 v91, v91, v214
	v_exp_f32_e32 v88, v88
	v_exp_f32_e32 v89, v89
	v_add_f32_e32 v36, v82, v36
	v_add_f32_e32 v37, v83, v37
	v_exp_f32_e32 v90, v90
	v_exp_f32_e32 v91, v91
	v_sub_f32_e32 v96, v108, v214
	v_sub_f32_e32 v97, v109, v214
	v_add_f32_e32 v36, v84, v36
	v_add_f32_e32 v37, v85, v37
	v_sub_f32_e32 v92, v92, v214
	v_sub_f32_e32 v93, v93, v214
	v_exp_f32_e32 v96, v96
	v_exp_f32_e32 v97, v97
	v_add_f32_e32 v36, v86, v36
	v_add_f32_e32 v37, v87, v37
	v_exp_f32_e32 v92, v92
	v_exp_f32_e32 v93, v93
	v_add_f32_e32 v36, v88, v36
	v_add_f32_e32 v37, v89, v37
	v_sub_f32_e32 v94, v94, v214
	v_sub_f32_e32 v95, v95, v214
	v_add_f32_e32 v36, v90, v36
	v_add_f32_e32 v37, v91, v37
	v_exp_f32_e32 v94, v94
	v_add_f32_e32 v36, v96, v36
	v_add_f32_e32 v37, v97, v37
	v_exp_f32_e32 v95, v95
	v_add_f32_e32 v98, v92, v36
	v_add_f32_e32 v99, v93, v37
	v_sub_f32_e32 v36, v110, v214
	v_sub_f32_e32 v37, v111, v214
	v_add_u32_e32 v33, s49, v223
	v_exp_f32_e32 v100, v36
	v_exp_f32_e32 v101, v37
	v_add_u32_e32 v108, 0x8800, v33
	v_add_u32_e32 v109, 0x9800, v33
	v_cvt_pk_bf16_f32 v34, v34, v35
	v_cvt_pk_bf16_f32 v35, v38, v39
	v_cvt_pk_bf16_f32 v36, v40, v41
	v_cvt_pk_bf16_f32 v37, v80, v81
	v_cvt_pk_bf16_f32 v38, v84, v85
	v_cvt_pk_bf16_f32 v39, v88, v89
	v_cvt_pk_bf16_f32 v40, v96, v97
	v_cvt_pk_bf16_f32 v41, v100, v101
	v_cvt_pk_bf16_f32 v42, v42, v43
	v_cvt_pk_bf16_f32 v43, v44, v45
	v_cvt_pk_bf16_f32 v44, v46, v47
	v_cvt_pk_bf16_f32 v45, v82, v83
	v_cvt_pk_bf16_f32 v80, v86, v87
	v_cvt_pk_bf16_f32 v81, v90, v91
	v_cvt_pk_bf16_f32 v82, v92, v93
	v_cvt_pk_bf16_f32 v83, v94, v95
	s_setprio 0
	s_barrier
	ds_read2_b64 v[84:87], v108 offset1:2
	ds_read2_b64 v[88:91], v109 offset0:32 offset1:34
	v_add_f32_e32 v46, v100, v98
	v_add_f32_e32 v47, v101, v99
	s_nop 0
	v_add_f32_e32 v46, v94, v46
	v_add_f32_e32 v47, v95, v47
	s_nop 0
	v_add_f32_e32 v46, v46, v47
	v_add_f32_e32 v250, v250, v46
	v_add_u32_e32 v46, 0xa800, v33
	v_add_u32_e32 v33, 0xb800, v33
	ds_read2_b64 v[92:95], v46 offset0:64 offset1:66
	ds_read2_b64 v[96:99], v33 offset0:96 offset1:98
	ds_read2_b64 v[100:103], v108 offset0:4 offset1:6
	ds_read2_b64 v[104:107], v109 offset0:36 offset1:38
	s_waitcnt lgkmcnt(5)
	v_mfma_f32_32x32x16_bf16 v[64:79], v[84:87], v[34:37], v[64:79]
	s_waitcnt lgkmcnt(4)
	v_mfma_f32_32x32x16_bf16 v[48:63], v[88:91], v[34:37], v[48:63]
	ds_read2_b64 v[84:87], v46 offset0:68 offset1:70
	ds_read2_b64 v[88:91], v33 offset0:100 offset1:102
	s_waitcnt lgkmcnt(5)
	v_mfma_f32_32x32x16_bf16 v[16:31], v[92:95], v[34:37], v[16:31]
	s_waitcnt lgkmcnt(4)
	v_mfma_f32_32x32x16_bf16 v[0:15], v[96:99], v[34:37], v[0:15]
	ds_read2_b64 v[34:37], v108 offset0:8 offset1:10
	ds_read2_b64 v[92:95], v109 offset0:40 offset1:42
	s_waitcnt lgkmcnt(5)
	v_mfma_f32_32x32x16_bf16 v[64:79], v[100:103], v[38:41], v[64:79]
	s_waitcnt lgkmcnt(4)
	v_mfma_f32_32x32x16_bf16 v[48:63], v[104:107], v[38:41], v[48:63]
	ds_read2_b64 v[96:99], v46 offset0:72 offset1:74
	ds_read2_b64 v[100:103], v33 offset0:104 offset1:106
	s_waitcnt lgkmcnt(5)
	v_mfma_f32_32x32x16_bf16 v[16:31], v[84:87], v[38:41], v[16:31]
	s_waitcnt lgkmcnt(4)
	v_mfma_f32_32x32x16_bf16 v[0:15], v[88:91], v[38:41], v[0:15]
	ds_read2_b64 v[38:41], v108 offset0:12 offset1:14
	ds_read2_b64 v[84:87], v109 offset0:44 offset1:46
	s_waitcnt lgkmcnt(5)
	v_mfma_f32_32x32x16_bf16 v[64:79], v[34:37], v[42:45], v[64:79]
	s_waitcnt lgkmcnt(4)
	v_mfma_f32_32x32x16_bf16 v[48:63], v[92:95], v[42:45], v[48:63]
	ds_read2_b64 v[34:37], v46 offset0:76 offset1:78
	ds_read2_b64 v[88:91], v33 offset0:108 offset1:110
	s_waitcnt lgkmcnt(5)
	v_mfma_f32_32x32x16_bf16 v[16:31], v[96:99], v[42:45], v[16:31]
	s_waitcnt lgkmcnt(4)
	v_mfma_f32_32x32x16_bf16 v[0:15], v[100:103], v[42:45], v[0:15]
	s_waitcnt lgkmcnt(3)
	v_mfma_f32_32x32x16_bf16 v[64:79], v[38:41], v[80:83], v[64:79]
	s_waitcnt lgkmcnt(2)
	v_mfma_f32_32x32x16_bf16 v[48:63], v[84:87], v[80:83], v[48:63]
	s_waitcnt lgkmcnt(1)
	v_mfma_f32_32x32x16_bf16 v[16:31], v[34:37], v[80:83], v[16:31]
	s_waitcnt lgkmcnt(0)
	v_mfma_f32_32x32x16_bf16 v[0:15], v[88:91], v[80:83], v[0:15]

;     __device__ __forceinline__ void fused(f32x4 (&acc)[2][2][4][2], const Unit& u, int wr, int wc, int fr, int fq, PG8_LAS unsigned char* lds, int wid, int lane) const {
;     ...
;         asm volatile("s_waitcnt vmcnt(0) lgkmcnt(0)" ::: "memory"); __builtin_amdgcn_s_barrier(); asm volatile("" ::: "memory");
;         if (lane < 32) {
;             const float* slot = xbuf + (size_t)(u.pm * BM + row) * 4; float q[4];
; #pragma unroll
;             for (int c = 0; c < 4; ++c) { float v = 0.f;
; #pragma unroll
;                 for (int t = 0; t < 4; ++t) v += __hip_atomic_load(slot + (size_t)c * 16384 * 4 + t, __ATOMIC_RELAXED, __HIP_MEMORY_SCOPE_AGENT);
;                 q[c] = v; }
;             const float r1 = 1.0f / sqrtf(q[0] * (1.0f / 1024.0f) + eps);
;             const float ss2 = q[1] + 2.0f * r1 * q[2] + r1 * r1 * q[3];
;             S[row] = (f32x2v){r1, 1.0f / sqrtf(fmaxf(ss2, 0.f) * (1.0f / 1024.0f) + eps)};
.LBB0_856:
	s_waitcnt vmcnt(0) lgkmcnt(0)
	s_barrier
	s_and_saveexec_b64 s[6:7], s[40:41]
	s_cbranch_execz .LBB0_858
	v_lshl_add_u64 v[148:149], v[148:149], 4, s[26:27]
	s_waitcnt lgkmcnt(0)
	v_add_co_u32_e32 v150, vcc, 0x40000, v148
	s_nop 1
	v_addc_co_u32_e32 v151, vcc, 0, v149, vcc
	v_add_co_u32_e32 v206, vcc, 0x80000, v148
	s_nop 1
	v_addc_co_u32_e32 v207, vcc, 0, v149, vcc
	global_load_dword v208, v[148:149], off sc1
	global_load_dword v209, v[148:149], off offset:4 sc1
	global_load_dword v210, v[148:149], off offset:8 sc1
	global_load_dword v211, v[148:149], off offset:12 sc1
	global_load_dword v212, v[150:151], off sc1
	global_load_dword v213, v[150:151], off offset:4 sc1
	global_load_dword v214, v[150:151], off offset:8 sc1
	global_load_dword v215, v[150:151], off offset:12 sc1
	v_add_co_u32_e32 v148, vcc, 0xc0000, v148
	s_nop 1
	v_addc_co_u32_e32 v149, vcc, 0, v149, vcc
	global_load_dword v152, v[206:207], off sc1
	global_load_dword v154, v[206:207], off offset:4 sc1
	global_load_dword v156, v[206:207], off offset:8 sc1
	global_load_dword v216, v[206:207], off offset:12 sc1
	global_load_dword v153, v[148:149], off sc1
	global_load_dword v155, v[148:149], off offset:4 sc1
	global_load_dword v157, v[148:149], off offset:8 sc1
	global_load_dword v217, v[148:149], off offset:12 sc1
	s_mov_b32 s17, 0xf800000
	s_mov_b32 s73, 0xf800000
	v_lshl_add_u32 v33, v33, 3, 0
	s_waitcnt vmcnt(12)
	v_add_f32_e32 v219, 0, v208
	v_add_f32_e32 v219, v219, v209
	v_add_f32_e32 v219, v219, v210
	v_add_f32_e32 v158, v219, v211
	s_waitcnt vmcnt(8)
	v_add_f32_e32 v218, 0, v212
	v_add_f32_e32 v218, v218, v213
	v_add_f32_e32 v218, v218, v214
	v_add_f32_e32 v159, v218, v215
	v_fmamk_f32 v148, v158, 0x3a800000, v231
	v_cmp_gt_f32_e32 vcc, s17, v148
	v_mul_f32_e32 v149, 0x4f800000, v148
	s_waitcnt vmcnt(3)
	v_pk_add_f32 v[152:153], v[152:153], 0 op_sel_hi:[1,0]
	v_cndmask_b32_e32 v148, v148, v149, vcc
	v_sqrt_f32_e32 v149, v148
	s_waitcnt vmcnt(2)
	v_pk_add_f32 v[152:153], v[152:153], v[154:155]
	v_add_u32_e32 v158, -1, v149
	v_fma_f32 v160, -v158, v149, v148
	v_cmp_ge_f32_e64 s[40:41], 0, v160
	v_add_u32_e32 v160, 1, v149
	s_waitcnt vmcnt(1)
	v_pk_add_f32 v[152:153], v[152:153], v[156:157]
	v_cndmask_b32_e64 v158, v149, v158, s[40:41]
	v_fma_f32 v149, -v160, v149, v148
	v_cmp_lt_f32_e64 s[40:41], 0, v149
	s_waitcnt vmcnt(0)
	v_pk_add_f32 v[150:151], v[152:153], v[216:217]
	v_cndmask_b32_e64 v149, v158, v160, s[40:41]
	v_mul_f32_e32 v158, 0x37800000, v149
	v_cndmask_b32_e32 v149, v149, v158, vcc
	v_cmp_class_f32_e32 vcc, v148, v232
	s_nop 1
	v_cndmask_b32_e32 v148, v149, v148, vcc
	v_div_scale_f32 v149, s[4:5], v148, v148, 1.0
	v_rcp_f32_e32 v158, v149
	s_nop 0
	v_fma_f32 v160, -v149, v158, 1.0
	v_fmac_f32_e32 v158, v160, v158
	v_div_scale_f32 v160, vcc, 1.0, v148, 1.0
	v_mul_f32_e32 v161, v160, v158
	v_fma_f32 v162, -v149, v161, v160
	v_fmac_f32_e32 v161, v162, v158
	v_fma_f32 v149, -v149, v161, v160
	v_div_fmas_f32 v149, v149, v158, v161
	v_div_fixup_f32 v148, v149, v148, 1.0
	v_mov_b32_e32 v195, v148
	v_pk_mul_f32 v[152:153], v[148:149], v[194:195] op_sel_hi:[0,1]
	v_pk_mul_f32 v[150:151], v[152:153], v[150:151]
	s_nop 0
	v_add_f32_e32 v149, v159, v150
	v_add_f32_e32 v149, v149, v151
	v_max_f32_e32 v149, 0, v149
	v_fmamk_f32 v149, v149, 0x3a800000, v231
	v_cmp_gt_f32_e32 vcc, s17, v149
	v_mul_f32_e32 v150, 0x4f800000, v149
	s_nop 0
	v_cndmask_b32_e32 v149, v149, v150, vcc
	v_sqrt_f32_e32 v150, v149
	s_nop 0
	v_add_u32_e32 v151, -1, v150
	v_fma_f32 v152, -v151, v150, v149
	v_cmp_ge_f32_e64 s[40:41], 0, v152
	v_add_u32_e32 v152, 1, v150
	s_nop 0
	v_cndmask_b32_e64 v151, v150, v151, s[40:41]
	v_fma_f32 v150, -v152, v150, v149
	v_cmp_lt_f32_e64 s[40:41], 0, v150
	s_nop 1
	v_cndmask_b32_e64 v150, v151, v152, s[40:41]
	v_mul_f32_e32 v151, 0x37800000, v150
	v_cndmask_b32_e32 v150, v150, v151, vcc
	v_cmp_class_f32_e32 vcc, v149, v232
	s_nop 1
	v_cndmask_b32_e32 v149, v150, v149, vcc
	v_div_scale_f32 v150, s[4:5], v149, v149, 1.0
	v_rcp_f32_e32 v151, v150
	s_nop 0
	v_fma_f32 v152, -v150, v151, 1.0
	v_fmac_f32_e32 v151, v152, v151
	v_div_scale_f32 v152, vcc, 1.0, v149, 1.0
	v_mul_f32_e32 v153, v152, v151
	v_fma_f32 v154, -v150, v153, v152
	v_fmac_f32_e32 v153, v154, v151
	v_fma_f32 v150, -v150, v153, v152
	v_div_fmas_f32 v150, v150, v151, v153
	v_div_fixup_f32 v149, v150, v149, 1.0
	ds_write_b64 v33, v[148:149] offset:16384

;     __device__ __forceinline__ void fused(f32x4 (&acc)[2][2][4][2], const Unit& u, int wr, int wc, int fr, int fq, PG8_LAS unsigned char* lds, int wid, int lane) const {
;     ...
;         asm volatile("s_waitcnt vmcnt(0) lgkmcnt(0)" ::: "memory"); __builtin_amdgcn_s_barrier(); asm volatile("" ::: "memory");
;         if (lane < 32) {
;             const float* slot = xbuf + (size_t)(u.pm * BM + row) * 4; float q[4];
; #pragma unroll
;             for (int c = 0; c < 4; ++c) { float v = 0.f;
; #pragma unroll
;                 for (int t = 0; t < 4; ++t) v += __hip_atomic_load(slot + (size_t)c * 16384 * 4 + t, __ATOMIC_RELAXED, __HIP_MEMORY_SCOPE_AGENT);
;                 q[c] = v; }
;             const float r1 = 1.0f / sqrtf(q[0] * (1.0f / 1024.0f) + eps);
;             const float ss2 = q[1] + 2.0f * r1 * q[2] + r1 * r1 * q[3];
;             S[row] = (f32x2v){r1, 1.0f / sqrtf(fmaxf(ss2, 0.f) * (1.0f / 1024.0f) + eps)};
.LBB0_1113:
	s_waitcnt vmcnt(0) lgkmcnt(0)
	s_barrier
	s_and_saveexec_b64 s[6:7], s[40:41]
	s_cbranch_execz .LBB0_1115
	v_lshl_add_u64 v[148:149], v[148:149], 4, s[30:31]
	s_waitcnt lgkmcnt(0)
	v_add_co_u32_e32 v150, vcc, 0x40000, v148
	s_nop 1
	v_addc_co_u32_e32 v151, vcc, 0, v149, vcc
	v_add_co_u32_e32 v206, vcc, 0x80000, v148
	s_nop 1
	v_addc_co_u32_e32 v207, vcc, 0, v149, vcc
	global_load_dword v208, v[148:149], off sc1
	global_load_dword v209, v[148:149], off offset:4 sc1
	global_load_dword v210, v[148:149], off offset:8 sc1
	global_load_dword v211, v[148:149], off offset:12 sc1
	global_load_dword v212, v[150:151], off sc1
	global_load_dword v213, v[150:151], off offset:4 sc1
	global_load_dword v214, v[150:151], off offset:8 sc1
	global_load_dword v215, v[150:151], off offset:12 sc1
	v_add_co_u32_e32 v148, vcc, 0xc0000, v148
	s_nop 1
	v_addc_co_u32_e32 v149, vcc, 0, v149, vcc
	global_load_dword v152, v[206:207], off sc1
	global_load_dword v154, v[206:207], off offset:4 sc1
	global_load_dword v156, v[206:207], off offset:8 sc1
	global_load_dword v216, v[206:207], off offset:12 sc1
	global_load_dword v153, v[148:149], off sc1
	global_load_dword v155, v[148:149], off offset:4 sc1
	global_load_dword v157, v[148:149], off offset:8 sc1
	global_load_dword v217, v[148:149], off offset:12 sc1
	s_mov_b32 s16, 0xf800000
	s_mov_b32 s73, 0xf800000
	v_lshl_add_u32 v33, v33, 3, 0
	s_waitcnt vmcnt(12)
	v_add_f32_e32 v219, 0, v208
	v_add_f32_e32 v219, v219, v209
	v_add_f32_e32 v219, v219, v210
	v_add_f32_e32 v158, v219, v211
	s_waitcnt vmcnt(8)
	v_add_f32_e32 v218, 0, v212
	v_add_f32_e32 v218, v218, v213
	v_add_f32_e32 v218, v218, v214
	v_add_f32_e32 v159, v218, v215
	v_fmamk_f32 v148, v158, 0x3a800000, v231
	v_cmp_gt_f32_e32 vcc, s16, v148
	v_mul_f32_e32 v149, 0x4f800000, v148
	s_waitcnt vmcnt(3)
	v_pk_add_f32 v[152:153], v[152:153], 0 op_sel_hi:[1,0]
	v_cndmask_b32_e32 v148, v148, v149, vcc
	v_sqrt_f32_e32 v149, v148
	s_waitcnt vmcnt(2)
	v_pk_add_f32 v[152:153], v[152:153], v[154:155]
	v_add_u32_e32 v158, -1, v149
	v_fma_f32 v160, -v158, v149, v148
	v_cmp_ge_f32_e64 s[40:41], 0, v160
	v_add_u32_e32 v160, 1, v149
	s_waitcnt vmcnt(1)
	v_pk_add_f32 v[152:153], v[152:153], v[156:157]
	v_cndmask_b32_e64 v158, v149, v158, s[40:41]
	v_fma_f32 v149, -v160, v149, v148
	v_cmp_lt_f32_e64 s[40:41], 0, v149
	s_waitcnt vmcnt(0)
	v_pk_add_f32 v[150:151], v[152:153], v[216:217]
	v_cndmask_b32_e64 v149, v158, v160, s[40:41]
	v_mul_f32_e32 v158, 0x37800000, v149
	v_cndmask_b32_e32 v149, v149, v158, vcc
	v_cmp_class_f32_e32 vcc, v148, v232
	s_nop 1
	v_cndmask_b32_e32 v148, v149, v148, vcc
	v_div_scale_f32 v149, s[4:5], v148, v148, 1.0
	v_rcp_f32_e32 v158, v149
	s_nop 0
	v_fma_f32 v160, -v149, v158, 1.0
	v_fmac_f32_e32 v158, v160, v158
	v_div_scale_f32 v160, vcc, 1.0, v148, 1.0
	v_mul_f32_e32 v161, v160, v158
	v_fma_f32 v162, -v149, v161, v160
	v_fmac_f32_e32 v161, v162, v158
	v_fma_f32 v149, -v149, v161, v160
	v_div_fmas_f32 v149, v149, v158, v161
	v_div_fixup_f32 v148, v149, v148, 1.0
	v_mov_b32_e32 v195, v148
	v_pk_mul_f32 v[152:153], v[148:149], v[194:195] op_sel_hi:[0,1]
	v_pk_mul_f32 v[150:151], v[152:153], v[150:151]
	s_nop 0
	v_add_f32_e32 v149, v159, v150
	v_add_f32_e32 v149, v149, v151
	v_max_f32_e32 v149, 0, v149
	v_fmamk_f32 v149, v149, 0x3a800000, v231
	v_cmp_gt_f32_e32 vcc, s16, v149
	v_mul_f32_e32 v150, 0x4f800000, v149
	s_nop 0
	v_cndmask_b32_e32 v149, v149, v150, vcc
	v_sqrt_f32_e32 v150, v149
	s_nop 0
	v_add_u32_e32 v151, -1, v150
	v_fma_f32 v152, -v151, v150, v149
	v_cmp_ge_f32_e64 s[40:41], 0, v152
	v_add_u32_e32 v152, 1, v150
	s_nop 0
	v_cndmask_b32_e64 v151, v150, v151, s[40:41]
	v_fma_f32 v150, -v152, v150, v149
	v_cmp_lt_f32_e64 s[40:41], 0, v150
	s_nop 1
	v_cndmask_b32_e64 v150, v151, v152, s[40:41]
	v_mul_f32_e32 v151, 0x37800000, v150
	v_cndmask_b32_e32 v150, v150, v151, vcc
	v_cmp_class_f32_e32 vcc, v149, v232
	s_nop 1
	v_cndmask_b32_e32 v149, v150, v149, vcc
	v_div_scale_f32 v150, s[4:5], v149, v149, 1.0
	v_rcp_f32_e32 v151, v150
	s_nop 0
	v_fma_f32 v152, -v150, v151, 1.0
	v_fmac_f32_e32 v151, v152, v151
	v_div_scale_f32 v152, vcc, 1.0, v149, 1.0
	v_mul_f32_e32 v153, v152, v151
	v_fma_f32 v154, -v150, v153, v152
	v_fmac_f32_e32 v153, v154, v151
	v_fma_f32 v150, -v150, v153, v152
	v_div_fmas_f32 v150, v150, v151, v153
	v_div_fixup_f32 v149, v150, v149, 1.0
	ds_write_b64 v33, v[148:149] offset:16384
